# selected-block attention: a wave whose 32 query rows did not select the staged block skips scores/softmax/PV for it (stabiliser-only difference)
# baseline (speedup 1.0000x reference)
.Lmy_tramp4:
	s_branch .LBB0_4
	s_nop 0
	s_nop 0
	s_nop 0
	s_nop 0
	s_nop 0
	s_nop 0
	s_nop 0
	s_nop 0
	s_nop 0
	s_nop 0
	s_nop 0
	s_nop 0
	s_nop 0
	s_nop 0
	s_nop 0
	s_nop 0
	s_nop 0
	s_nop 0
	s_nop 0
	s_nop 0
	s_nop 0
	s_nop 0
	s_nop 0
	s_nop 0
	s_nop 0
	s_nop 0
	s_nop 0
	s_nop 0
	s_nop 0
	s_nop 0
	s_nop 0
	s_nop 0
	s_nop 0
	s_nop 0
.Lmy_pad_cmp:
	s_nop 6
	v_mul_f32_e32 v8, 0x3d372713, v2
	v_mul_f32_e32 v9, 0x3d372713, v3
	v_mul_f32_e32 v10, 0x3d372713, v4
	v_mul_f32_e32 v11, 0x3d372713, v5
	v_mul_f32_e32 v8, v2, v8
	v_mul_f32_e32 v9, v3, v9
	v_mul_f32_e32 v10, v4, v10
	v_mul_f32_e32 v11, v5, v11
	v_fma_f32 v8, v2, v8, v2
	v_fma_f32 v9, v3, v9, v3
	v_fma_f32 v10, v4, v10, v4
	v_fma_f32 v11, v5, v11, v5
	v_mul_f32_e32 v8, 0xbfcc422a, v8
	v_mul_f32_e32 v9, 0xbfcc422a, v9
	v_mul_f32_e32 v10, 0xbfcc422a, v10
	v_mul_f32_e32 v11, 0xbfcc422a, v11
	v_mul_f32_e32 v8, 0x3fb8aa3b, v8
	v_mul_f32_e32 v9, 0x3fb8aa3b, v9
	v_mul_f32_e32 v10, 0x3fb8aa3b, v10
	v_mul_f32_e32 v11, 0x3fb8aa3b, v11
	v_exp_f32_e32 v8, v8
	v_exp_f32_e32 v9, v9
	v_exp_f32_e32 v10, v10
	v_exp_f32_e32 v11, v11
	v_add_f32_e32 v8, 1.0, v8
	v_add_f32_e32 v9, 1.0, v9
	v_add_f32_e32 v10, 1.0, v10
	v_add_f32_e32 v11, 1.0, v11
	v_rcp_f32_e32 v8, v8
	v_rcp_f32_e32 v9, v9
	v_rcp_f32_e32 v10, v10
	v_rcp_f32_e32 v11, v11
	s_and_b32 s14, s14, 3
	v_pk_mul_f32 v[2:3], v[2:3], v[8:9]
	v_or_b32_e32 v6, v34, v35
	v_pk_mul_f32 v[4:5], v[4:5], v[10:11]
	s_lshl_b64 s[10:11], s[10:11], 15
	v_readlane_b32 s15, v252, 27
	v_cvt_pk_bf16_f32 v2, v2, v3
	v_cvt_pk_bf16_f32 v3, v4, v5
	v_mad_u32_u24 v12, v35, s64, 0
	v_lshlrev_b32_e32 v4, 1, v34
	v_ashrrev_i32_e32 v7, 31, v6
	s_add_u32 s10, s15, s10
	v_readlane_b32 s15, v252, 28
	v_add3_u32 v4, v12, v4, v14
	s_addc_u32 s11, s15, s11
	ds_write_b64 v4, v[2:3] offset:16384
	v_lshlrev_b64 v[2:3], 8, v[6:7]
	v_lshl_add_u64 v[2:3], s[10:11], 0, v[2:3]
	v_lshlrev_b32_e32 v10, 1, v14
	v_mov_b32_e32 v11, v0
	v_lshl_add_u64 v[2:3], v[2:3], 0, v[10:11]
	s_waitcnt lgkmcnt(0)
	s_barrier
	global_load_dwordx4 v[26:29], v[2:3], off
	global_load_dwordx4 v[14:17], v[2:3], off offset:64
	global_load_dwordx4 v[6:9], v[2:3], off offset:128
	s_nop 0
	global_load_dwordx4 v[2:5], v[2:3], off offset:192
	v_add_u32_e32 v10, v12, v10
	ds_read_b128 v[30:33], v10 offset:16384
	ds_read_b128 v[22:25], v10 offset:16448
	ds_read_b128 v[18:21], v10 offset:16512
	ds_read_b128 v[10:13], v10 offset:16576
	s_cmpk_lt_u32 s4, 0x100
	s_mov_b64 s[10:11], -1
	s_cbranch_scc1 .LBB0_89
	s_waitcnt vmcnt(3) lgkmcnt(3)
	v_mfma_f32_16x16x32_bf16 v[36:39], v[30:33], v[26:29], 0
	v_readlane_b32 s10, v252, 21
	v_readlane_b32 s2, v252, 56
	v_readlane_b32 s11, v252, 22
	s_waitcnt vmcnt(2) lgkmcnt(2)
	v_mfma_f32_16x16x32_bf16 v[36:39], v[22:25], v[14:17], v[36:39]
	v_readlane_b32 s3, v252, 57
	s_mov_b32 s9, s3
	s_lshl_b32 s8, s12, 1
	s_waitcnt vmcnt(1) lgkmcnt(1)
	v_mfma_f32_16x16x32_bf16 v[36:39], v[18:21], v[6:9], v[36:39]
	v_writelane_b32 v252, s2, 56
	s_waitcnt vmcnt(0) lgkmcnt(0)
	v_mfma_f32_16x16x32_bf16 v[36:39], v[10:13], v[2:5], v[36:39]
	v_writelane_b32 v252, s3, 57
	s_nop 6
	v_cvt_pk_bf16_f32 v36, v36, v37
	v_cvt_pk_bf16_f32 v37, v38, v39
	v_lshl_or_b32 v38, s13, 9, v35
	v_lshl_or_b32 v38, s14, 7, v38
	v_add_u32_e32 v38, v38, v34
	v_ashrrev_i32_e32 v39, 31, v38
	v_lshlrev_b64 v[38:39], 9, v[38:39]
	v_lshl_add_u64 v[38:39], s[10:11], 0, v[38:39]
	v_lshl_add_u64 v[38:39], v[38:39], 0, s[8:9]
	s_mov_b64 s[10:11], 0

.LBB0_116:
	s_lshl_b64 s[20:21], s[20:21], 1
	v_mov_b32_dpp v42, v42 wave_ror:1 row_mask:0xf bank_mask:0xf
	v_cmp_eq_f32_e64 s[18:19], v42, v39
	v_cmp_gt_f32_e64 s[16:17], v42, v39
	s_and_b64 s[18:19], s[18:19], s[20:21]
	s_or_b64 s[16:17], s[16:17], s[18:19]
	v_addc_co_u32_e64 v41, s[16:17], 0, v41, s[16:17]
	s_lshl_b64 s[20:21], s[20:21], 1
	v_mov_b32_dpp v42, v42 wave_ror:1 row_mask:0xf bank_mask:0xf
	v_cmp_eq_f32_e64 s[18:19], v42, v39
	v_cmp_gt_f32_e64 s[16:17], v42, v39
	s_and_b64 s[18:19], s[18:19], s[20:21]
	s_or_b64 s[16:17], s[16:17], s[18:19]
	v_addc_co_u32_e64 v41, s[16:17], 0, v41, s[16:17]
	s_lshl_b64 s[20:21], s[20:21], 1
	v_mov_b32_dpp v42, v42 wave_ror:1 row_mask:0xf bank_mask:0xf
	v_cmp_eq_f32_e64 s[18:19], v42, v39
	v_cmp_gt_f32_e64 s[16:17], v42, v39
	s_and_b64 s[18:19], s[18:19], s[20:21]
	s_or_b64 s[16:17], s[16:17], s[18:19]
	v_addc_co_u32_e64 v41, s[16:17], 0, v41, s[16:17]
	s_lshl_b64 s[20:21], s[20:21], 1
	v_mov_b32_dpp v42, v42 wave_ror:1 row_mask:0xf bank_mask:0xf
	v_cmp_eq_f32_e64 s[18:19], v42, v39
	v_cmp_gt_f32_e64 s[16:17], v42, v39
	s_and_b64 s[18:19], s[18:19], s[20:21]
	s_or_b64 s[16:17], s[16:17], s[18:19]
	v_addc_co_u32_e64 v41, s[16:17], 0, v41, s[16:17]
	s_lshl_b64 s[20:21], s[20:21], 1
	v_mov_b32_dpp v42, v42 wave_ror:1 row_mask:0xf bank_mask:0xf
	v_cmp_eq_f32_e64 s[18:19], v42, v39
	v_cmp_gt_f32_e64 s[16:17], v42, v39
	s_and_b64 s[18:19], s[18:19], s[20:21]
	s_or_b64 s[16:17], s[16:17], s[18:19]
	v_addc_co_u32_e64 v41, s[16:17], 0, v41, s[16:17]
	s_lshl_b64 s[20:21], s[20:21], 1
	v_mov_b32_dpp v42, v42 wave_ror:1 row_mask:0xf bank_mask:0xf
	v_cmp_eq_f32_e64 s[18:19], v42, v39
	v_cmp_gt_f32_e64 s[16:17], v42, v39
	s_and_b64 s[18:19], s[18:19], s[20:21]
	s_or_b64 s[16:17], s[16:17], s[18:19]
	v_addc_co_u32_e64 v41, s[16:17], 0, v41, s[16:17]
	s_lshl_b64 s[20:21], s[20:21], 1
	v_mov_b32_dpp v42, v42 wave_ror:1 row_mask:0xf bank_mask:0xf
	v_cmp_eq_f32_e64 s[18:19], v42, v39
	v_cmp_gt_f32_e64 s[16:17], v42, v39
	s_and_b64 s[18:19], s[18:19], s[20:21]
	s_or_b64 s[16:17], s[16:17], s[18:19]
	v_addc_co_u32_e64 v41, s[16:17], 0, v41, s[16:17]
	s_add_i32 s5, s5, 1
	s_cmp_eq_u32 s5, 9
	s_cbranch_scc0 .LBB0_116
	s_branch .Lmy_rank_done
.Lmy_rank_done:
	v_cmp_gt_u32_e64 s[16:17], 16, v41
	s_and_b64 s[16:17], s[16:17], s[14:15]
	s_nop 0
	v_cndmask_b32_e64 v39, 0, 1, s[16:17]
	v_cmp_ne_u32_e64 s[18:19], 0, v39
	s_and_saveexec_b64 s[16:17], vcc
	s_cbranch_execz .LBB0_114
	v_lshl_add_u32 v38, v38, 3, 0
	v_add_u32_e32 v38, 0x21c00, v38
	v_mov_b64_e32 v[40:41], s[18:19]
	ds_write_b64 v38, v[40:41]
	s_branch .LBB0_114

.LBB0_127:
	s_lshl_b64 s[12:13], 1, s24
	s_cmp_ge_i32 s24, s40
	v_lshl_or_b32 v1, s24, 6, v207
	s_cselect_b64 s[24:25], -1, 0
	s_cmp_eq_u32 s31, 0
	s_cselect_b32 s14, 0, 0x11c00
	v_sub_u32_e32 v211, 0, v1
	v_add_u32_e32 v1, s14, v192
	v_and_b32_e32 v115, s13, v181
	v_and_b32_e32 v114, s12, v180
	v_add_u32_e32 v212, v1, v198
	v_cmp_ne_u64_e64 s[10:11], 0, v[114:115]
	v_or_b32_e32 v114, v180, v182
	v_or_b32_e32 v115, v181, v183
	v_and_b32_e32 v114, s12, v114
	v_and_b32_e32 v115, s13, v115
	v_cmp_ne_u64_e32 vcc, 0, v[114:115]
	s_nop 0
	s_and_b64 vcc, exec, vcc
	s_cbranch_vccz .Lmy_sel_skip
	ds_read_b128 v[220:223], v212
	ds_read_b128 v[244:247], v212 offset:64
	ds_read_b128 v[248:251], v212 offset:128
	s_and_b64 vcc, exec, s[24:25]
	s_waitcnt lgkmcnt(2)
	v_mfma_f32_16x16x32_bf16 v[130:133], v[220:223], v[2:5], 0
	v_mfma_f32_16x16x32_bf16 v[114:117], v[220:223], v[18:21], 0
	ds_read_b128 v[220:223], v212 offset:192
	s_waitcnt lgkmcnt(2)
	v_mfma_f32_16x16x32_bf16 v[130:133], v[244:247], v[6:9], v[130:133]
	v_mfma_f32_16x16x32_bf16 v[114:117], v[244:247], v[22:25], v[114:117]
	ds_read_b128 v[244:247], v212 offset:4352
	s_waitcnt lgkmcnt(2)
	v_mfma_f32_16x16x32_bf16 v[130:133], v[248:251], v[10:13], v[130:133]
	v_mfma_f32_16x16x32_bf16 v[114:117], v[248:251], v[26:29], v[114:117]
	ds_read_b128 v[248:251], v212 offset:4416
	s_waitcnt lgkmcnt(2)
	v_mfma_f32_16x16x32_bf16 v[130:133], v[220:223], v[14:17], v[130:133]
	v_mfma_f32_16x16x32_bf16 v[114:117], v[220:223], v[30:33], v[114:117]
	ds_read_b128 v[220:223], v212 offset:4480
	s_waitcnt lgkmcnt(2)
	v_mfma_f32_16x16x32_bf16 v[134:137], v[244:247], v[2:5], 0
	v_mfma_f32_16x16x32_bf16 v[118:121], v[244:247], v[18:21], 0
	ds_read_b128 v[244:247], v212 offset:4544
	s_waitcnt lgkmcnt(2)
	v_mfma_f32_16x16x32_bf16 v[134:137], v[248:251], v[6:9], v[134:137]
	v_mfma_f32_16x16x32_bf16 v[118:121], v[248:251], v[22:25], v[118:121]
	ds_read_b128 v[248:251], v212 offset:8704
	s_waitcnt lgkmcnt(2)
	v_mfma_f32_16x16x32_bf16 v[134:137], v[220:223], v[10:13], v[134:137]
	v_mfma_f32_16x16x32_bf16 v[118:121], v[220:223], v[26:29], v[118:121]
	ds_read_b128 v[220:223], v212 offset:8768
	s_waitcnt lgkmcnt(2)
	v_mfma_f32_16x16x32_bf16 v[134:137], v[244:247], v[14:17], v[134:137]
	v_mfma_f32_16x16x32_bf16 v[118:121], v[244:247], v[30:33], v[118:121]
	ds_read_b128 v[244:247], v212 offset:8832
	s_waitcnt lgkmcnt(2)
	v_mfma_f32_16x16x32_bf16 v[138:141], v[248:251], v[2:5], 0
	v_mfma_f32_16x16x32_bf16 v[122:125], v[248:251], v[18:21], 0
	ds_read_b128 v[248:251], v212 offset:8896
	s_waitcnt lgkmcnt(2)
	v_mfma_f32_16x16x32_bf16 v[138:141], v[220:223], v[6:9], v[138:141]
	v_mfma_f32_16x16x32_bf16 v[122:125], v[220:223], v[22:25], v[122:125]
	ds_read_b128 v[220:223], v212 offset:13056
	s_waitcnt lgkmcnt(2)
	v_mfma_f32_16x16x32_bf16 v[138:141], v[244:247], v[10:13], v[138:141]
	v_mfma_f32_16x16x32_bf16 v[122:125], v[244:247], v[26:29], v[122:125]
	ds_read_b128 v[244:247], v212 offset:13120
	s_waitcnt lgkmcnt(2)
	v_mfma_f32_16x16x32_bf16 v[138:141], v[248:251], v[14:17], v[138:141]
	v_mfma_f32_16x16x32_bf16 v[122:125], v[248:251], v[30:33], v[122:125]
	ds_read_b128 v[248:251], v212 offset:13184
	s_waitcnt lgkmcnt(2)
	v_mfma_f32_16x16x32_bf16 v[142:145], v[220:223], v[2:5], 0
	v_mfma_f32_16x16x32_bf16 v[126:129], v[220:223], v[18:21], 0
	ds_read_b128 v[220:223], v212 offset:13248
	s_waitcnt lgkmcnt(2)
	v_mfma_f32_16x16x32_bf16 v[142:145], v[244:247], v[6:9], v[142:145]
	v_mfma_f32_16x16x32_bf16 v[126:129], v[244:247], v[22:25], v[126:129]
	s_waitcnt lgkmcnt(1)
	v_mfma_f32_16x16x32_bf16 v[142:145], v[248:251], v[10:13], v[142:145]
	v_mfma_f32_16x16x32_bf16 v[126:129], v[248:251], v[26:29], v[126:129]
	s_waitcnt lgkmcnt(0)
	v_mfma_f32_16x16x32_bf16 v[142:145], v[220:223], v[14:17], v[142:145]
	v_mfma_f32_16x16x32_bf16 v[126:129], v[220:223], v[30:33], v[126:129]
	s_cbranch_vccz .LBB0_129
	v_add_u32_e32 v212, v211, v208
	v_cndmask_b32_e64 v220, v229, 0, s[10:11]
	v_cndmask_b32_e64 v213, v228, 0, s[10:11]
	v_cmp_lt_i32_e32 vcc, v212, v220
	v_sub_u32_e32 v212, v212, v220
	s_nop 0
	v_cndmask_b32_e32 v213, v213, v230, vcc
	v_cndmask_b32_e64 v212, v212, 0, vcc
	v_cmp_le_u32_e32 vcc, v213, v212
	v_or_b32_e32 v220, 2, v213
	s_nop 0
	v_cndmask_b32_e32 v130, v227, v130, vcc
	v_cmp_lt_u32_e32 vcc, v213, v212
	s_nop 1
	v_cndmask_b32_e32 v131, v227, v131, vcc
	v_cmp_le_u32_e32 vcc, v220, v212
	v_or_b32_e32 v220, 3, v213
	s_nop 0
	v_cndmask_b32_e32 v132, v227, v132, vcc
	v_cmp_le_u32_e32 vcc, v220, v212
	v_add_u32_e32 v220, 16, v213
	s_nop 0
	v_cndmask_b32_e32 v133, v227, v133, vcc
	v_cmp_le_u32_e32 vcc, v220, v212
	v_add_u32_e32 v220, 17, v213
	s_nop 0
	v_cndmask_b32_e32 v134, v227, v134, vcc
	v_cmp_le_u32_e32 vcc, v220, v212
	v_add_u32_e32 v220, 18, v213
	s_nop 0
	v_cndmask_b32_e32 v135, v227, v135, vcc
	v_cmp_le_u32_e32 vcc, v220, v212
	v_add_u32_e32 v220, 19, v213
	s_nop 0
	v_cndmask_b32_e32 v136, v227, v136, vcc
	v_cmp_le_u32_e32 vcc, v220, v212
	v_add_u32_e32 v220, 32, v213
	s_nop 0
	v_cndmask_b32_e32 v137, v227, v137, vcc
	v_cmp_le_u32_e32 vcc, v220, v212
	v_add_u32_e32 v220, 33, v213
	s_nop 0
	v_cndmask_b32_e32 v138, v227, v138, vcc
	v_cmp_le_u32_e32 vcc, v220, v212
	v_add_u32_e32 v220, 34, v213
	s_nop 0
	v_cndmask_b32_e32 v139, v227, v139, vcc
	v_cmp_le_u32_e32 vcc, v220, v212
	v_add_u32_e32 v220, 35, v213
	s_nop 0
	v_cndmask_b32_e32 v140, v227, v140, vcc
	v_cmp_le_u32_e32 vcc, v220, v212
	v_add_u32_e32 v220, 48, v213
	s_nop 0
	v_cndmask_b32_e32 v141, v227, v141, vcc
	v_cmp_le_u32_e32 vcc, v220, v212
	v_add_u32_e32 v220, 49, v213
	s_nop 0
	v_cndmask_b32_e32 v142, v227, v142, vcc
	v_cmp_le_u32_e32 vcc, v220, v212
	v_add_u32_e32 v220, 50, v213
	v_add_u32_e32 v213, 51, v213
	v_cndmask_b32_e32 v143, v227, v143, vcc
	v_cmp_le_u32_e32 vcc, v220, v212
	s_nop 1
	v_cndmask_b32_e32 v144, v227, v144, vcc
	v_cmp_le_u32_e32 vcc, v213, v212
	s_nop 1
	v_cndmask_b32_e32 v145, v227, v145, vcc

.Lmy_sel_cont:
	s_mov_b32 s24, s17
	s_mov_b32 s17, s34
	s_branch .LBB0_124
.Lmy_sel_skip:
	v_cndmask_b32_e64 v1, 0, 1, s[22:23]
	s_andn2_b64 vcc, exec, s[20:21]
	s_nop 0
	v_readfirstlane_b32 s10, v1
	s_xor_b32 s31, s31, s10
	s_waitcnt lgkmcnt(0)
	s_barrier
	s_cbranch_vccz .LBB0_136
	s_branch .Lmy_sel_cont
